# speedup vs baseline: 1.0034x; 1.0034x over previous
; DI_ unsigned pk2(float lo, float hi) { typedef float f2 __attribute__((ext_vector_type(2))); typedef __bf16 b2 __attribute__((ext_vector_type(2))); f2 v = {lo, hi}; b2 b = __builtin_convertvector(v, b2); return __builtin_bit_cast(unsigned, b); }
; DI_ float silu_f(float v) { return v / (1.f + __expf(-v)); }
; DI_ void ssm_conv_tile(int tile, const unsigned char* buf, unsigned char* obuf, const float* cw, const float* cbias, bf16_t* xsT, bf16_t* Btok, bf16_t* BT, bf16_t* Ctok, int tid) {
;     ...
;     const float w0 = cw[chg], w1 = cw[4096 + chg], w2 = cw[2 * 4096 + chg], w3 = cw[3 * 4096 + chg], bb = cbias[chg];
;     const bf16_t* col = (const bf16_t*)buf + ch;
;     float x0 = __uint_as_float((unsigned)col[(tl0 + 0) * 64] << 16), x1 = __uint_as_float((unsigned)col[(tl0 + 1) * 64] << 16), x2 = __uint_as_float((unsigned)col[(tl0 + 2) * 64] << 16);
;     float y[16];
; #pragma unroll
;     for (int i = 0; i < 16; ++i) { const float x3 = __uint_as_float((unsigned)col[(tl0 + 3 + i) * 64] << 16); const float v = bb + w0 * x0 + w1 * x1 + w2 * x2 + w3 * x3; y[i] = silu_f(v); x0 = x1; x1 = x2; x2 = x3; }
;     u32x4 o0, o1; o0.x = pk2(y[0], y[1]); o0.y = pk2(y[2], y[3]); o0.z = pk2(y[4], y[5]); o0.w = pk2(y[6], y[7]); o1.x = pk2(y[8], y[9]); o1.y = pk2(y[10], y[11]); o1.z = pk2(y[12], y[13]); o1.w = pk2(y[14], y[15]);
.LBB0_565:
	s_and_b32 s8, s26, 0xfc0
	s_nop 0
	s_cmpk_lt_u32 s8, 0xc00
	s_nop 0
	s_nop 0
	ds_read_u16 v46, v39 offset:1792
	ds_read_u16 v51, v39 offset:2048
	ds_read_u16 v47, v43
	ds_read_u16 v55, v39 offset:2176
	ds_read_u16 v53, v39 offset:2304
	ds_read_u16 v58, v39 offset:1536
	ds_read_u16 v59, v39 offset:1664
	ds_read_u16 v62, v39 offset:1280
	ds_read_u16 v63, v39 offset:1408
	ds_read_u16 v66, v39 offset:1024
	ds_read_u16 v67, v39 offset:1152
	ds_read_u16 v70, v39 offset:768
	ds_read_u16 v71, v39 offset:896
	ds_read_u16 v74, v39 offset:512
	ds_read_u16 v75, v39 offset:640
	s_cselect_b64 s[10:11], -1, 0
	s_cmpk_gt_u32 s8, 0xbff
	s_waitcnt lgkmcnt(10)
	v_lshlrev_b32_e32 v46, 16, v46
	v_lshlrev_b32_e32 v51, 16, v51
	ds_read_u16 v88, v39 offset:256
	ds_read_u16 v89, v39 offset:384
	ds_read_u16 v90, v39
	ds_read_u16 v91, v39 offset:128
	v_lshlrev_b32_e32 v47, 16, v47
	v_mov_b32_e32 v50, v47
	v_mov_b32_e32 v54, v51
	v_lshlrev_b32_e32 v55, 16, v55
	v_lshlrev_b32_e32 v53, 16, v53
	s_waitcnt lgkmcnt(12)
	v_lshlrev_b32_e32 v58, 16, v58
	v_lshlrev_b32_e32 v59, 16, v59
	s_waitcnt vmcnt(3)
	v_mov_b32_e32 v36, v242
	v_mov_b32_e32 v38, v243
	v_mov_b32_e32 v40, v244
	v_mov_b32_e32 v42, v245
	v_mov_b32_e32 v44, v246
	v_pk_fma_f32 v[56:57], v[36:37], v[58:59], v[44:45] op_sel_hi:[0,1,0]
	s_waitcnt lgkmcnt(10)
	v_lshlrev_b32_e32 v62, 16, v62
	v_lshlrev_b32_e32 v63, 16, v63
	v_pk_fma_f32 v[60:61], v[36:37], v[62:63], v[44:45] op_sel_hi:[0,1,0]
	s_waitcnt lgkmcnt(8)
	v_lshlrev_b32_e32 v66, 16, v66
	v_lshlrev_b32_e32 v67, 16, v67
	v_pk_fma_f32 v[64:65], v[36:37], v[66:67], v[44:45] op_sel_hi:[0,1,0]
	s_waitcnt lgkmcnt(6)
	v_lshlrev_b32_e32 v70, 16, v70
	v_lshlrev_b32_e32 v71, 16, v71
	v_pk_fma_f32 v[68:69], v[36:37], v[70:71], v[44:45] op_sel_hi:[0,1,0]
	s_waitcnt lgkmcnt(4)
	v_lshlrev_b32_e32 v74, 16, v74
	v_lshlrev_b32_e32 v75, 16, v75
	v_pk_fma_f32 v[72:73], v[36:37], v[74:75], v[44:45] op_sel_hi:[0,1,0]
	s_waitcnt lgkmcnt(2)
	v_lshlrev_b32_e32 v88, 16, v88
	v_lshlrev_b32_e32 v89, 16, v89
	v_pk_fma_f32 v[76:77], v[36:37], v[88:89], v[44:45] op_sel_hi:[0,1,0]
	v_pk_mov_b32 v[94:95], v[88:89], v[74:75] op_sel:[1,0]
	s_waitcnt lgkmcnt(0)
	v_lshlrev_b32_e32 v90, 16, v90
	v_lshlrev_b32_e32 v91, 16, v91
	v_pk_fma_f32 v[92:93], v[36:37], v[90:91], v[44:45] op_sel_hi:[0,1,0]
	v_pk_mov_b32 v[90:91], v[90:91], v[88:89] op_sel:[1,0]
	v_pk_fma_f32 v[76:77], v[38:39], v[94:95], v[76:77] op_sel_hi:[0,1,1]
	v_pk_fma_f32 v[90:91], v[38:39], v[90:91], v[92:93] op_sel_hi:[0,1,1]
	v_pk_fma_f32 v[88:89], v[40:41], v[88:89], v[90:91] op_sel_hi:[0,1,1]
	v_pk_fma_f32 v[88:89], v[42:43], v[94:95], v[88:89] op_sel_hi:[0,1,1]
	v_mul_f32_e32 v37, 0xbfb8aa3b, v88
	v_exp_f32_e32 v90, v37
	v_mul_f32_e32 v37, 0xbfb8aa3b, v89
	v_exp_f32_e32 v91, v37
	s_nop 0
	v_pk_add_f32 v[90:91], v[90:91], 1.0 op_sel_hi:[1,0]
	s_nop 0
	v_rcp_f32_e32 v49, v91
	s_nop 0
	v_mul_f32_e32 v87, v89, v49
	v_mov_b32_e32 v37, v87
	v_rcp_f32_e32 v52, v90
	v_mov_b32_e32 v37, v37
	v_mul_f32_e32 v49, v88, v52
	v_pk_mov_b32 v[88:89], v[74:75], v[70:71] op_sel:[1,0]
	v_pk_fma_f32 v[74:75], v[40:41], v[74:75], v[76:77] op_sel_hi:[0,1,1]
	v_pk_fma_f32 v[76:77], v[42:43], v[88:89], v[74:75] op_sel_hi:[0,1,1]
	v_mul_f32_e32 v52, 0xbfb8aa3b, v76
	v_exp_f32_e32 v74, v52
	v_mul_f32_e32 v52, 0xbfb8aa3b, v77
	v_exp_f32_e32 v75, v52
	v_pk_fma_f32 v[72:73], v[38:39], v[88:89], v[72:73] op_sel_hi:[0,1,1]
	v_pk_add_f32 v[90:91], v[74:75], 1.0 op_sel_hi:[1,0]
	s_nop 0
	v_rcp_f32_e32 v74, v91
	s_nop 0
	v_mul_f32_e32 v74, v77, v74
	v_rcp_f32_e32 v75, v90
	s_nop 0
	v_mul_f32_e32 v75, v76, v75
	v_pk_mov_b32 v[76:77], v[70:71], v[66:67] op_sel:[1,0]
	v_pk_fma_f32 v[70:71], v[40:41], v[70:71], v[72:73] op_sel_hi:[0,1,1]
	v_pk_fma_f32 v[72:73], v[42:43], v[76:77], v[70:71] op_sel_hi:[0,1,1]
	v_mul_f32_e32 v52, 0xbfb8aa3b, v72
	v_exp_f32_e32 v70, v52
	v_mul_f32_e32 v52, 0xbfb8aa3b, v73
	v_exp_f32_e32 v71, v52
	v_pk_fma_f32 v[68:69], v[38:39], v[76:77], v[68:69] op_sel_hi:[0,1,1]
	v_pk_add_f32 v[88:89], v[70:71], 1.0 op_sel_hi:[1,0]
	s_nop 0
	v_rcp_f32_e32 v70, v89
	s_nop 0
	v_mul_f32_e32 v70, v73, v70
	v_rcp_f32_e32 v71, v88
	s_nop 0
	v_mul_f32_e32 v71, v72, v71
	v_pk_mov_b32 v[72:73], v[66:67], v[62:63] op_sel:[1,0]
	v_pk_fma_f32 v[66:67], v[40:41], v[66:67], v[68:69] op_sel_hi:[0,1,1]
	v_pk_fma_f32 v[68:69], v[42:43], v[72:73], v[66:67] op_sel_hi:[0,1,1]
	v_mul_f32_e32 v52, 0xbfb8aa3b, v68
	v_exp_f32_e32 v66, v52
	v_mul_f32_e32 v52, 0xbfb8aa3b, v69
	v_exp_f32_e32 v67, v52
	v_pk_fma_f32 v[64:65], v[38:39], v[72:73], v[64:65] op_sel_hi:[0,1,1]
	v_pk_add_f32 v[76:77], v[66:67], 1.0 op_sel_hi:[1,0]
	s_nop 0
	v_rcp_f32_e32 v66, v77
	s_nop 0
	v_mul_f32_e32 v66, v69, v66
	v_rcp_f32_e32 v67, v76
	s_nop 0
	v_mul_f32_e32 v67, v68, v67
	v_pk_mov_b32 v[68:69], v[62:63], v[58:59] op_sel:[1,0]
	v_pk_fma_f32 v[62:63], v[40:41], v[62:63], v[64:65] op_sel_hi:[0,1,1]
	v_pk_fma_f32 v[64:65], v[42:43], v[68:69], v[62:63] op_sel_hi:[0,1,1]
	v_mul_f32_e32 v52, 0xbfb8aa3b, v64
	v_exp_f32_e32 v62, v52
	v_mul_f32_e32 v52, 0xbfb8aa3b, v65
	v_exp_f32_e32 v63, v52
	v_pk_fma_f32 v[60:61], v[38:39], v[68:69], v[60:61] op_sel_hi:[0,1,1]
	v_pk_add_f32 v[72:73], v[62:63], 1.0 op_sel_hi:[1,0]
	s_nop 0
	v_rcp_f32_e32 v62, v73
	s_nop 0
	v_mul_f32_e32 v62, v65, v62
	v_rcp_f32_e32 v63, v72
	s_nop 0
	v_mul_f32_e32 v63, v64, v63
	v_pk_mov_b32 v[64:65], v[58:59], v[46:47] op_sel:[1,0]
	v_pk_fma_f32 v[58:59], v[40:41], v[58:59], v[60:61] op_sel_hi:[0,1,1]
	v_pk_fma_f32 v[60:61], v[42:43], v[64:65], v[58:59] op_sel_hi:[0,1,1]
	v_mul_f32_e32 v52, 0xbfb8aa3b, v60
	v_exp_f32_e32 v58, v52
	v_mul_f32_e32 v52, 0xbfb8aa3b, v61
	v_exp_f32_e32 v59, v52
	v_pk_fma_f32 v[56:57], v[38:39], v[64:65], v[56:57] op_sel_hi:[0,1,1]
	v_pk_fma_f32 v[56:57], v[40:41], v[46:47], v[56:57] op_sel_hi:[0,1,1]
	v_pk_fma_f32 v[46:47], v[36:37], v[46:47], v[44:45] op_sel_hi:[0,1,0]
	v_pk_add_f32 v[68:69], v[58:59], 1.0 op_sel_hi:[1,0]
	v_pk_fma_f32 v[46:47], v[38:39], v[50:51], v[46:47] op_sel_hi:[0,1,1]
	v_rcp_f32_e32 v58, v69
	v_pk_fma_f32 v[46:47], v[40:41], v[54:55], v[46:47] op_sel_hi:[0,1,1]
	v_mul_f32_e32 v58, v61, v58
	v_rcp_f32_e32 v59, v68
	s_nop 0
	v_mul_f32_e32 v59, v60, v59
	v_pk_fma_f32 v[60:61], v[42:43], v[50:51], v[56:57] op_sel_hi:[0,1,1]
	v_mul_f32_e32 v52, 0xbfb8aa3b, v60
	v_exp_f32_e32 v56, v52
	v_mul_f32_e32 v52, 0xbfb8aa3b, v61
	v_exp_f32_e32 v57, v52
	s_nop 0
	v_pk_add_f32 v[64:65], v[56:57], 1.0 op_sel_hi:[1,0]
	s_nop 0
	v_rcp_f32_e32 v56, v65
	s_nop 0
	v_mul_f32_e32 v56, v61, v56
	v_rcp_f32_e32 v57, v64
	s_nop 0
	v_mul_f32_e32 v57, v60, v57
	v_mov_b32_e32 v52, v55
	v_pk_fma_f32 v[46:47], v[42:43], v[52:53], v[46:47] op_sel_hi:[0,1,1]
	v_mul_f32_e32 v36, 0xbfb8aa3b, v46
	v_exp_f32_e32 v50, v36
	v_mul_f32_e32 v36, 0xbfb8aa3b, v47
	v_exp_f32_e32 v51, v36
	s_nop 0
	v_pk_add_f32 v[50:51], v[50:51], 1.0 op_sel_hi:[1,0]
	s_nop 0
	v_rcp_f32_e32 v38, v51
	s_nop 0
	v_mul_f32_e32 v42, v47, v38
	v_mov_b32_e32 v36, v42
	v_rcp_f32_e32 v40, v50
	v_mov_b32_e32 v36, v36
	v_mul_f32_e32 v38, v46, v40
	s_cbranch_scc1 .LBB0_567
; DI_ unsigned pk2(float lo, float hi) { typedef float f2 __attribute__((ext_vector_type(2))); typedef __bf16 b2 __attribute__((ext_vector_type(2))); f2 v = {lo, hi}; b2 b = __builtin_convertvector(v, b2); return __builtin_bit_cast(unsigned, b); }
; DI_ void ssm_conv_tile(int tile, const unsigned char* buf, unsigned char* obuf, const float* cw, const float* cbias, bf16_t* xsT, bf16_t* Btok, bf16_t* BT, bf16_t* Ctok, int tid) {
;     ...
;     u32x4 o0, o1; o0.x = pk2(y[0], y[1]); o0.y = pk2(y[2], y[3]); o0.z = pk2(y[4], y[5]); o0.w = pk2(y[6], y[7]); o1.x = pk2(y[8], y[9]); o1.y = pk2(y[10], y[11]); o1.z = pk2(y[12], y[13]); o1.w = pk2(y[14], y[15]);
;     const int tg0 = tb + tl0;
;     unsigned char* obuf2 = obuf + 16384;
;     const bool chmaj = ch0 < 3072, tokmaj = ch0 >= 2048;
;     if (chmaj) { *(u32x4*)(obuf2 + ch * 272 + tl0 * 2) = o0; *(u32x4*)(obuf2 + ch * 272 + tl0 * 2 + 16) = o1; }
	v_cvt_pk_bf16_f32 v50, v49, v37
	v_cvt_pk_bf16_f32 v51, v75, v74
	v_cvt_pk_bf16_f32 v52, v71, v70
	v_cvt_pk_bf16_f32 v53, v67, v66
	v_add_u32_e32 v40, v45, v78
	v_cvt_pk_bf16_f32 v88, v63, v62
	v_cvt_pk_bf16_f32 v89, v59, v58
	v_cvt_pk_bf16_f32 v90, v57, v56
	v_cvt_pk_bf16_f32 v91, v38, v36
	ds_write_b128 v40, v[50:53] offset:49920
	ds_write_b128 v40, v[88:91] offset:49936

; DI_ float silu_f(float v) { return v / (1.f + __expf(-v)); }
; DI_ void ssm_conv_tile(int tile, const unsigned char* buf, unsigned char* obuf, const float* cw, const float* cbias, bf16_t* xsT, bf16_t* Btok, bf16_t* BT, bf16_t* Ctok, int tid) {
;     ...
;     const bf16_t* col = (const bf16_t*)buf + ch;
;     float x0 = __uint_as_float((unsigned)col[(tl0 + 0) * 64] << 16), x1 = __uint_as_float((unsigned)col[(tl0 + 1) * 64] << 16), x2 = __uint_as_float((unsigned)col[(tl0 + 2) * 64] << 16);
;     float y[16];
; #pragma unroll
;     for (int i = 0; i < 16; ++i) { const float x3 = __uint_as_float((unsigned)col[(tl0 + 3 + i) * 64] << 16); const float v = bb + w0 * x0 + w1 * x1 + w2 * x2 + w3 * x3; y[i] = silu_f(v); x0 = x1; x1 = x2; x2 = x3; }
.LBB0_588:
	v_readlane_b32 s4, v254, 11
	s_add_i32 s4, s4, s26
	s_and_b32 s8, s4, 0xfc0
	s_nop 0
	s_cmpk_lt_u32 s8, 0xc00
	s_nop 0
	s_nop 0
	ds_read_u16 v46, v39 offset:18560
	ds_read_u16 v47, v43 offset:16768
	ds_read_u16 v51, v39 offset:18816
	ds_read_u16 v55, v39 offset:18944
	ds_read_u16 v53, v39 offset:19072
	ds_read_u16 v58, v39 offset:18304
	ds_read_u16 v59, v39 offset:18432
	ds_read_u16 v62, v39 offset:18048
	ds_read_u16 v63, v39 offset:18176
	ds_read_u16 v66, v39 offset:17792
	ds_read_u16 v67, v39 offset:17920
	ds_read_u16 v70, v39 offset:17536
	ds_read_u16 v71, v39 offset:17664
	ds_read_u16 v74, v39 offset:17280
	ds_read_u16 v75, v39 offset:17408
	s_cselect_b64 s[10:11], -1, 0
	s_cmpk_gt_u32 s8, 0xbff
	s_waitcnt lgkmcnt(10)
	v_lshlrev_b32_e32 v47, 16, v47
	v_lshlrev_b32_e32 v46, 16, v46
	ds_read_u16 v88, v39 offset:17024
	ds_read_u16 v89, v39 offset:17152
	ds_read_u16 v90, v39 offset:16768
	ds_read_u16 v91, v39 offset:16896
	v_mov_b32_e32 v50, v47
	v_lshlrev_b32_e32 v51, 16, v51
	v_mov_b32_e32 v54, v51
	v_lshlrev_b32_e32 v55, 16, v55
	v_lshlrev_b32_e32 v53, 16, v53
	s_waitcnt lgkmcnt(12)
	v_lshlrev_b32_e32 v58, 16, v58
	v_lshlrev_b32_e32 v59, 16, v59
	s_waitcnt vmcnt(3)
	v_mov_b32_e32 v36, v242
	v_mov_b32_e32 v38, v243
	v_mov_b32_e32 v40, v244
	v_mov_b32_e32 v42, v245
	v_mov_b32_e32 v44, v246
	v_pk_fma_f32 v[56:57], v[36:37], v[58:59], v[44:45] op_sel_hi:[0,1,0]
	s_waitcnt lgkmcnt(10)
	v_lshlrev_b32_e32 v62, 16, v62
	v_lshlrev_b32_e32 v63, 16, v63
	v_pk_fma_f32 v[60:61], v[36:37], v[62:63], v[44:45] op_sel_hi:[0,1,0]
	s_waitcnt lgkmcnt(8)
	v_lshlrev_b32_e32 v66, 16, v66
	v_lshlrev_b32_e32 v67, 16, v67
	v_pk_fma_f32 v[64:65], v[36:37], v[66:67], v[44:45] op_sel_hi:[0,1,0]
	s_waitcnt lgkmcnt(6)
	v_lshlrev_b32_e32 v70, 16, v70
	v_lshlrev_b32_e32 v71, 16, v71
	v_pk_fma_f32 v[68:69], v[36:37], v[70:71], v[44:45] op_sel_hi:[0,1,0]
	s_waitcnt lgkmcnt(4)
	v_lshlrev_b32_e32 v74, 16, v74
	v_lshlrev_b32_e32 v75, 16, v75
	v_pk_fma_f32 v[72:73], v[36:37], v[74:75], v[44:45] op_sel_hi:[0,1,0]
	s_waitcnt lgkmcnt(2)
	v_lshlrev_b32_e32 v88, 16, v88
	v_lshlrev_b32_e32 v89, 16, v89
	v_pk_fma_f32 v[76:77], v[36:37], v[88:89], v[44:45] op_sel_hi:[0,1,0]
	v_pk_mov_b32 v[94:95], v[88:89], v[74:75] op_sel:[1,0]
	s_waitcnt lgkmcnt(0)
; DI_ unsigned pk2(float lo, float hi) { typedef float f2 __attribute__((ext_vector_type(2))); typedef __bf16 b2 __attribute__((ext_vector_type(2))); f2 v = {lo, hi}; b2 b = __builtin_convertvector(v, b2); return __builtin_bit_cast(unsigned, b); }
; DI_ float silu_f(float v) { return v / (1.f + __expf(-v)); }
; DI_ void ssm_conv_tile(int tile, const unsigned char* buf, unsigned char* obuf, const float* cw, const float* cbias, bf16_t* xsT, bf16_t* Btok, bf16_t* BT, bf16_t* Ctok, int tid) {
;     ...
;     for (int i = 0; i < 16; ++i) { const float x3 = __uint_as_float((unsigned)col[(tl0 + 3 + i) * 64] << 16); const float v = bb + w0 * x0 + w1 * x1 + w2 * x2 + w3 * x3; y[i] = silu_f(v); x0 = x1; x1 = x2; x2 = x3; }
;     u32x4 o0, o1; o0.x = pk2(y[0], y[1]); o0.y = pk2(y[2], y[3]); o0.z = pk2(y[4], y[5]); o0.w = pk2(y[6], y[7]); o1.x = pk2(y[8], y[9]); o1.y = pk2(y[10], y[11]); o1.z = pk2(y[12], y[13]); o1.w = pk2(y[14], y[15]);
;     const int tg0 = tb + tl0;
;     unsigned char* obuf2 = obuf + 16384;
;     const bool chmaj = ch0 < 3072, tokmaj = ch0 >= 2048;
;     if (chmaj) { *(u32x4*)(obuf2 + ch * 272 + tl0 * 2) = o0; *(u32x4*)(obuf2 + ch * 272 + tl0 * 2 + 16) = o1; }
	v_lshlrev_b32_e32 v90, 16, v90
	v_lshlrev_b32_e32 v91, 16, v91
	v_pk_fma_f32 v[92:93], v[36:37], v[90:91], v[44:45] op_sel_hi:[0,1,0]
	v_pk_mov_b32 v[90:91], v[90:91], v[88:89] op_sel:[1,0]
	v_pk_fma_f32 v[76:77], v[38:39], v[94:95], v[76:77] op_sel_hi:[0,1,1]
	v_pk_fma_f32 v[90:91], v[38:39], v[90:91], v[92:93] op_sel_hi:[0,1,1]
	v_pk_fma_f32 v[88:89], v[40:41], v[88:89], v[90:91] op_sel_hi:[0,1,1]
	v_pk_fma_f32 v[88:89], v[42:43], v[94:95], v[88:89] op_sel_hi:[0,1,1]
	v_mul_f32_e32 v37, 0xbfb8aa3b, v88
	v_exp_f32_e32 v90, v37
	v_mul_f32_e32 v37, 0xbfb8aa3b, v89
	v_exp_f32_e32 v91, v37
	s_nop 0
	v_pk_add_f32 v[90:91], v[90:91], 1.0 op_sel_hi:[1,0]
	s_nop 0
	v_rcp_f32_e32 v49, v91
	s_nop 0
	v_mul_f32_e32 v87, v89, v49
	v_mov_b32_e32 v37, v87
	v_rcp_f32_e32 v52, v90
	v_mov_b32_e32 v37, v37
	v_mul_f32_e32 v49, v88, v52
	v_pk_mov_b32 v[88:89], v[74:75], v[70:71] op_sel:[1,0]
	v_pk_fma_f32 v[74:75], v[40:41], v[74:75], v[76:77] op_sel_hi:[0,1,1]
	v_pk_fma_f32 v[76:77], v[42:43], v[88:89], v[74:75] op_sel_hi:[0,1,1]
	v_mul_f32_e32 v52, 0xbfb8aa3b, v76
	v_exp_f32_e32 v74, v52
	v_mul_f32_e32 v52, 0xbfb8aa3b, v77
	v_exp_f32_e32 v75, v52
	v_pk_fma_f32 v[72:73], v[38:39], v[88:89], v[72:73] op_sel_hi:[0,1,1]
	v_pk_add_f32 v[90:91], v[74:75], 1.0 op_sel_hi:[1,0]
	s_nop 0
	v_rcp_f32_e32 v74, v91
	s_nop 0
	v_mul_f32_e32 v74, v77, v74
	v_rcp_f32_e32 v75, v90
	s_nop 0
	v_mul_f32_e32 v75, v76, v75
	v_pk_mov_b32 v[76:77], v[70:71], v[66:67] op_sel:[1,0]
	v_pk_fma_f32 v[70:71], v[40:41], v[70:71], v[72:73] op_sel_hi:[0,1,1]
	v_pk_fma_f32 v[72:73], v[42:43], v[76:77], v[70:71] op_sel_hi:[0,1,1]
	v_mul_f32_e32 v52, 0xbfb8aa3b, v72
	v_exp_f32_e32 v70, v52
	v_mul_f32_e32 v52, 0xbfb8aa3b, v73
	v_exp_f32_e32 v71, v52
	v_pk_fma_f32 v[68:69], v[38:39], v[76:77], v[68:69] op_sel_hi:[0,1,1]
	v_pk_add_f32 v[88:89], v[70:71], 1.0 op_sel_hi:[1,0]
	s_nop 0
	v_rcp_f32_e32 v70, v89
	s_nop 0
	v_mul_f32_e32 v70, v73, v70
	v_rcp_f32_e32 v71, v88
	s_nop 0
	v_mul_f32_e32 v71, v72, v71
	v_pk_mov_b32 v[72:73], v[66:67], v[62:63] op_sel:[1,0]
	v_pk_fma_f32 v[66:67], v[40:41], v[66:67], v[68:69] op_sel_hi:[0,1,1]
	v_pk_fma_f32 v[68:69], v[42:43], v[72:73], v[66:67] op_sel_hi:[0,1,1]
	v_mul_f32_e32 v52, 0xbfb8aa3b, v68
	v_exp_f32_e32 v66, v52
	v_mul_f32_e32 v52, 0xbfb8aa3b, v69
	v_exp_f32_e32 v67, v52
	v_pk_fma_f32 v[64:65], v[38:39], v[72:73], v[64:65] op_sel_hi:[0,1,1]
	v_pk_add_f32 v[76:77], v[66:67], 1.0 op_sel_hi:[1,0]
	s_nop 0
	v_rcp_f32_e32 v66, v77
	s_nop 0
	v_mul_f32_e32 v66, v69, v66
	v_rcp_f32_e32 v67, v76
	s_nop 0
	v_mul_f32_e32 v67, v68, v67
	v_pk_mov_b32 v[68:69], v[62:63], v[58:59] op_sel:[1,0]
	v_pk_fma_f32 v[62:63], v[40:41], v[62:63], v[64:65] op_sel_hi:[0,1,1]
	v_pk_fma_f32 v[64:65], v[42:43], v[68:69], v[62:63] op_sel_hi:[0,1,1]
	v_mul_f32_e32 v52, 0xbfb8aa3b, v64
	v_exp_f32_e32 v62, v52
	v_mul_f32_e32 v52, 0xbfb8aa3b, v65
	v_exp_f32_e32 v63, v52
	v_pk_fma_f32 v[60:61], v[38:39], v[68:69], v[60:61] op_sel_hi:[0,1,1]
	v_pk_add_f32 v[72:73], v[62:63], 1.0 op_sel_hi:[1,0]
	s_nop 0
	v_rcp_f32_e32 v62, v73
	s_nop 0
	v_mul_f32_e32 v62, v65, v62
	v_rcp_f32_e32 v63, v72
	s_nop 0
	v_mul_f32_e32 v63, v64, v63
	v_pk_mov_b32 v[64:65], v[58:59], v[46:47] op_sel:[1,0]
	v_pk_fma_f32 v[58:59], v[40:41], v[58:59], v[60:61] op_sel_hi:[0,1,1]
	v_pk_fma_f32 v[60:61], v[42:43], v[64:65], v[58:59] op_sel_hi:[0,1,1]
	v_mul_f32_e32 v52, 0xbfb8aa3b, v60
	v_exp_f32_e32 v58, v52
	v_mul_f32_e32 v52, 0xbfb8aa3b, v61
	v_exp_f32_e32 v59, v52
	v_pk_fma_f32 v[56:57], v[38:39], v[64:65], v[56:57] op_sel_hi:[0,1,1]
	v_pk_fma_f32 v[56:57], v[40:41], v[46:47], v[56:57] op_sel_hi:[0,1,1]
	v_pk_fma_f32 v[46:47], v[36:37], v[46:47], v[44:45] op_sel_hi:[0,1,0]
	v_pk_add_f32 v[68:69], v[58:59], 1.0 op_sel_hi:[1,0]
	v_pk_fma_f32 v[46:47], v[38:39], v[50:51], v[46:47] op_sel_hi:[0,1,1]
	v_rcp_f32_e32 v58, v69
	v_pk_fma_f32 v[46:47], v[40:41], v[54:55], v[46:47] op_sel_hi:[0,1,1]
	v_mul_f32_e32 v58, v61, v58
	v_rcp_f32_e32 v59, v68
	s_nop 0
	v_mul_f32_e32 v59, v60, v59
	v_pk_fma_f32 v[60:61], v[42:43], v[50:51], v[56:57] op_sel_hi:[0,1,1]
	v_mul_f32_e32 v52, 0xbfb8aa3b, v60
	v_exp_f32_e32 v56, v52
	v_mul_f32_e32 v52, 0xbfb8aa3b, v61
	v_exp_f32_e32 v57, v52
	s_nop 0
	v_pk_add_f32 v[64:65], v[56:57], 1.0 op_sel_hi:[1,0]
	s_nop 0
	v_rcp_f32_e32 v56, v65
	s_nop 0
	v_mul_f32_e32 v56, v61, v56
	v_rcp_f32_e32 v57, v64
	s_nop 0
	v_mul_f32_e32 v57, v60, v57
	v_mov_b32_e32 v52, v55
	v_pk_fma_f32 v[46:47], v[42:43], v[52:53], v[46:47] op_sel_hi:[0,1,1]
	v_mul_f32_e32 v36, 0xbfb8aa3b, v46
	v_exp_f32_e32 v50, v36
	v_mul_f32_e32 v36, 0xbfb8aa3b, v47
	v_exp_f32_e32 v51, v36
	s_nop 0
	v_pk_add_f32 v[50:51], v[50:51], 1.0 op_sel_hi:[1,0]
	s_nop 0
	v_rcp_f32_e32 v38, v51
	s_nop 0
	v_mul_f32_e32 v42, v47, v38
	v_mov_b32_e32 v36, v42
	v_rcp_f32_e32 v40, v50
	v_mov_b32_e32 v36, v36
	v_mul_f32_e32 v38, v46, v40
	s_cbranch_scc1 .LBB0_590
	v_cvt_pk_bf16_f32 v50, v49, v37
	v_cvt_pk_bf16_f32 v51, v75, v74
	v_cvt_pk_bf16_f32 v52, v71, v70
	v_cvt_pk_bf16_f32 v53, v67, v66
	v_add_u32_e32 v40, v45, v78
	v_cvt_pk_bf16_f32 v88, v63, v62
	v_cvt_pk_bf16_f32 v89, v59, v58
	v_cvt_pk_bf16_f32 v90, v57, v56
	v_cvt_pk_bf16_f32 v91, v38, v36
	ds_write_b128 v40, v[50:53] offset:49920
	ds_write_b128 v40, v[88:91] offset:49936
